# v17 + gate/up tile header: with 256 workgroups the next tile is (same token tile, column tile + 4), bypassing the generic next-tile arithmetic (two divisions, v_rcp + readfirstlane)
# speedup vs baseline: 1.0070x; 1.0026x over previous
;     __host__ __device__ bool next(int i, Unit& u) const {
;         const long L = (long)i * G + c; if (L >= nwg) return false;
;         int wgid = (int)L; { const int q = nwg / NXCD, r = nwg % NXCD, xcd = wgid % NXCD, off = wgid / NXCD; wgid = (xcd < r ? xcd * (q + 1) : r * (q + 1) + (xcd - r) * q) + off; }
;         const int nig = WGM * nN, gid = wgid / nig, fm = gid * WGM, gsz = (nM - fm) < WGM ? (nM - fm) : WGM;
;         u.pm = fm + ((wgid % nig) % gsz); u.pn = (wgid % nig) / gsz; return true;
;     }
.LBB0_178:
	s_add_i32 s63, s63, 1
	s_mul_i32 s2, s63, s71
	s_mul_hi_u32 s3, s63, s72
	s_add_i32 s3, s3, s2
	s_mul_i32 s2, s63, s72
	s_add_u32 s52, s2, s26
	s_addc_u32 s53, s3, s21
	v_cmp_gt_i64_e32 vcc, s[52:53], v[146:147]
	v_cmp_lt_i64_e64 s[2:3], s[52:53], v[144:145]
	s_cbranch_vccnz .LBB0_180
	s_cmp_lg_u32 s72, 0x100
	s_cbranch_scc1 .Lhdr_181_gen
	s_add_i32 s48, s5, 4
	s_mov_b32 s50, s4
	s_branch .LBB0_180
.Lhdr_181_gen:
	s_ashr_i32 s48, s52, 31
	s_lshr_b32 s48, s48, 29
	s_add_i32 s48, s52, s48
	s_ashr_i32 s49, s48, 3
	s_and_b32 s48, s48, -8
	s_sub_i32 s48, s52, s48
	s_cmp_lt_i32 s48, 0
	s_cselect_b32 s50, s23, 0xb0
	s_mul_i32 s48, s50, s48
	s_add_i32 s48, s48, s49
	s_mul_hi_i32 s49, s48, 0x2e8ba2e9
	s_lshr_b32 s50, s49, 31
	s_ashr_i32 s49, s49, 5
	s_add_i32 s49, s49, s50
	s_lshl_b32 s50, s49, 3
	s_sub_i32 s51, 64, s50
	s_min_i32 s51, s51, 8
	s_abs_i32 s52, s51
	v_cvt_f32_u32_e32 v0, s52
	s_sub_i32 s54, 0, s52
	s_mulk_i32 s49, 0xb0
	s_sub_i32 s49, s48, s49
	v_rcp_iflag_f32_e32 v0, v0
	s_abs_i32 s48, s49
	s_xor_b32 s53, s49, s51
	s_ashr_i32 s53, s53, 31
	v_mul_f32_e32 v0, 0x4f7ffffe, v0
	v_cvt_u32_f32_e32 v0, v0
	s_nop 0
	v_readfirstlane_b32 s55, v0
	s_mul_i32 s54, s54, s55
	s_mul_hi_u32 s54, s55, s54
	s_add_i32 s55, s55, s54
	s_mul_hi_u32 s54, s48, s55
	s_mul_i32 s55, s54, s52
	s_sub_i32 s48, s48, s55
	s_add_i32 s56, s54, 1
	s_sub_i32 s55, s48, s52
	s_cmp_ge_u32 s48, s52
	s_cselect_b32 s54, s56, s54
	s_cselect_b32 s48, s55, s48
	s_add_i32 s55, s54, 1
	s_cmp_ge_u32 s48, s52
	s_cselect_b32 s48, s55, s54
	s_xor_b32 s48, s48, s53
	s_sub_i32 s48, s48, s53
	s_mul_i32 s51, s48, s51
	s_sub_i32 s49, s49, s51
	s_add_i32 s50, s49, s50

;     __host__ __device__ bool next(int i, Unit& u) const {
;         const long L = (long)i * G + c; if (L >= nwg) return false;
;         int wgid = (int)L; { const int q = nwg / NXCD, r = nwg % NXCD, xcd = wgid % NXCD, off = wgid / NXCD; wgid = (xcd < r ? xcd * (q + 1) : r * (q + 1) + (xcd - r) * q) + off; }
;         const int nig = WGM * nN, gid = wgid / nig, fm = gid * WGM, gsz = (nM - fm) < WGM ? (nM - fm) : WGM;
;         u.pm = fm + ((wgid % nig) % gsz); u.pn = (wgid % nig) / gsz; return true;
;     }
.LBB0_765:
	s_add_i32 s44, s44, 1
	s_mul_i32 s6, s44, s64
	s_mul_hi_u32 s7, s44, s65
	s_add_i32 s7, s7, s6
	s_mul_i32 s6, s44, s65
	s_add_u32 s54, s6, s26
	s_addc_u32 s55, s7, s3
	v_cmp_gt_i64_e32 vcc, s[54:55], v[146:147]
	v_cmp_lt_i64_e64 s[6:7], s[54:55], v[144:145]
	s_cbranch_vccnz .LBB0_767
	s_cmp_lg_u32 s65, 0x100
	s_cbranch_scc1 .Lhdr_768_gen
	s_add_i32 s50, s9, 4
	s_mov_b32 s52, s8
	s_branch .LBB0_767
.Lhdr_768_gen:
	s_ashr_i32 s50, s54, 31
	s_lshr_b32 s50, s50, 29
	s_add_i32 s50, s54, s50
	s_ashr_i32 s51, s50, 3
	s_and_b32 s50, s50, -8
	s_sub_i32 s50, s54, s50
	s_cmp_lt_i32 s50, 0
	s_cselect_b32 s52, s4, 0xb0
	s_mul_i32 s50, s52, s50
	s_add_i32 s50, s50, s51
	s_mul_hi_i32 s51, s50, 0x2e8ba2e9
	s_lshr_b32 s52, s51, 31
	s_ashr_i32 s51, s51, 5
	s_add_i32 s51, s51, s52
	s_lshl_b32 s52, s51, 3
	s_sub_i32 s53, 64, s52
	s_min_i32 s53, s53, 8
	s_abs_i32 s54, s53
	v_cvt_f32_u32_e32 v0, s54
	s_sub_i32 s56, 0, s54
	s_mulk_i32 s51, 0xb0
	s_sub_i32 s51, s50, s51
	v_rcp_iflag_f32_e32 v0, v0
	s_abs_i32 s50, s51
	s_xor_b32 s55, s51, s53
	s_ashr_i32 s55, s55, 31
	v_mul_f32_e32 v0, 0x4f7ffffe, v0
	v_cvt_u32_f32_e32 v0, v0
	s_nop 0
	v_readfirstlane_b32 s57, v0
	s_mul_i32 s56, s56, s57
	s_mul_hi_u32 s56, s57, s56
	s_add_i32 s57, s57, s56
	s_mul_hi_u32 s56, s50, s57
	s_mul_i32 s57, s56, s54
	s_sub_i32 s50, s50, s57
	s_add_i32 s58, s56, 1
	s_sub_i32 s57, s50, s54
	s_cmp_ge_u32 s50, s54
	s_cselect_b32 s56, s58, s56
	s_cselect_b32 s50, s57, s50
	s_add_i32 s57, s56, 1
	s_cmp_ge_u32 s50, s54
	s_cselect_b32 s50, s57, s56
	s_xor_b32 s50, s50, s55
	s_sub_i32 s50, s50, s55
	s_mul_i32 s53, s50, s53
	s_sub_i32 s51, s51, s53
	s_add_i32 s52, s51, s52

;     __host__ __device__ bool next(int i, Unit& u) const {
;         const long L = (long)i * G + c; if (L >= nwg) return false;
;         int wgid = (int)L; { const int q = nwg / NXCD, r = nwg % NXCD, xcd = wgid % NXCD, off = wgid / NXCD; wgid = (xcd < r ? xcd * (q + 1) : r * (q + 1) + (xcd - r) * q) + off; }
;         const int nig = WGM * nN, gid = wgid / nig, fm = gid * WGM, gsz = (nM - fm) < WGM ? (nM - fm) : WGM;
;         u.pm = fm + ((wgid % nig) % gsz); u.pn = (wgid % nig) / gsz; return true;
;     }
.LBB0_947:
	s_add_i32 s45, s45, 1
	s_mul_i32 s6, s45, s64
	s_mul_hi_u32 s7, s45, s65
	s_add_i32 s7, s7, s6
	s_mul_i32 s6, s45, s65
	s_add_u32 s52, s6, s26
	s_addc_u32 s53, s7, s3
	v_cmp_gt_i64_e32 vcc, s[52:53], v[146:147]
	v_cmp_lt_i64_e64 s[6:7], s[52:53], v[144:145]
	s_cbranch_vccnz .LBB0_949
	s_cmp_lg_u32 s65, 0x100
	s_cbranch_scc1 .Lhdr_950_gen
	s_add_i32 s48, s9, 4
	s_mov_b32 s50, s8
	s_branch .LBB0_949
.Lhdr_950_gen:
	s_ashr_i32 s48, s52, 31
	s_lshr_b32 s48, s48, 29
	s_add_i32 s48, s52, s48
	s_ashr_i32 s49, s48, 3
	s_and_b32 s48, s48, -8
	s_sub_i32 s48, s52, s48
	s_cmp_lt_i32 s48, 0
	s_cselect_b32 s50, s4, 0xb0
	s_mul_i32 s48, s50, s48
	s_add_i32 s48, s48, s49
	s_mul_hi_i32 s49, s48, 0x2e8ba2e9
	s_lshr_b32 s50, s49, 31
	s_ashr_i32 s49, s49, 5
	s_add_i32 s49, s49, s50
	s_lshl_b32 s50, s49, 3
	s_sub_i32 s51, 64, s50
	s_min_i32 s51, s51, 8
	s_abs_i32 s52, s51
	v_cvt_f32_u32_e32 v0, s52
	s_sub_i32 s54, 0, s52
	s_mulk_i32 s49, 0xb0
	s_sub_i32 s49, s48, s49
	v_rcp_iflag_f32_e32 v0, v0
	s_abs_i32 s48, s49
	s_xor_b32 s53, s49, s51
	s_ashr_i32 s53, s53, 31
	v_mul_f32_e32 v0, 0x4f7ffffe, v0
	v_cvt_u32_f32_e32 v0, v0
	s_nop 0
	v_readfirstlane_b32 s55, v0
	s_mul_i32 s54, s54, s55
	s_mul_hi_u32 s54, s55, s54
	s_add_i32 s55, s55, s54
	s_mul_hi_u32 s54, s48, s55
	s_mul_i32 s55, s54, s52
	s_sub_i32 s48, s48, s55
	s_add_i32 s56, s54, 1
	s_sub_i32 s55, s48, s52
	s_cmp_ge_u32 s48, s52
	s_cselect_b32 s54, s56, s54
	s_cselect_b32 s48, s55, s48
	s_add_i32 s55, s54, 1
	s_cmp_ge_u32 s48, s52
	s_cselect_b32 s48, s55, s54
	s_xor_b32 s48, s48, s53
	s_sub_i32 s48, s48, s53
	s_mul_i32 s51, s48, s51
	s_sub_i32 s49, s49, s51
	s_add_i32 s50, s49, s50

;     __host__ __device__ bool next(int i, Unit& u) const {
;         const long L = (long)i * G + c; if (L >= nwg) return false;
;         int wgid = (int)L; { const int q = nwg / NXCD, r = nwg % NXCD, xcd = wgid % NXCD, off = wgid / NXCD; wgid = (xcd < r ? xcd * (q + 1) : r * (q + 1) + (xcd - r) * q) + off; }
;         const int nig = WGM * nN, gid = wgid / nig, fm = gid * WGM, gsz = (nM - fm) < WGM ? (nM - fm) : WGM;
;         u.pm = fm + ((wgid % nig) % gsz); u.pn = (wgid % nig) / gsz; return true;
;     }
.LBB0_1604:
	s_add_i32 s51, s51, 1
	s_mul_i32 s4, s51, s58
	s_mul_hi_u32 s5, s51, s59
	s_add_i32 s5, s5, s4
	s_mul_i32 s4, s51, s59
	s_add_u32 s36, s4, s26
	s_addc_u32 s37, s5, s3
	v_cmp_gt_i64_e32 vcc, s[36:37], v[146:147]
	v_cmp_lt_i64_e64 s[4:5], s[36:37], v[144:145]
	s_cbranch_vccnz .LBB0_1606
	s_cmp_lg_u32 s59, 0x100
	s_cbranch_scc1 .Lhdr_1607_gen
	s_add_i32 s22, s7, 4
	s_mov_b32 s24, s6
	s_branch .LBB0_1606
.Lhdr_1607_gen:
	s_ashr_i32 s22, s36, 31
	s_lshr_b32 s22, s22, 29
	s_add_i32 s22, s36, s22
	s_ashr_i32 s23, s22, 3
	s_and_b32 s22, s22, -8
	s_sub_i32 s22, s36, s22
	s_cmp_lt_i32 s22, 0
	s_cselect_b32 s24, s19, 0xb0
	s_mul_i32 s22, s24, s22
	s_add_i32 s22, s22, s23
	s_mul_hi_i32 s23, s22, 0x2e8ba2e9
	s_lshr_b32 s24, s23, 31
	s_ashr_i32 s23, s23, 5
	s_add_i32 s23, s23, s24
	s_lshl_b32 s24, s23, 3
	s_sub_i32 s25, 64, s24
	s_min_i32 s25, s25, 8
	s_abs_i32 s36, s25
	v_cvt_f32_u32_e32 v0, s36
	s_sub_i32 s42, 0, s36
	s_mulk_i32 s23, 0xb0
	s_sub_i32 s23, s22, s23
	v_rcp_iflag_f32_e32 v0, v0
	s_abs_i32 s22, s23
	s_xor_b32 s37, s23, s25
	s_ashr_i32 s37, s37, 31
	v_mul_f32_e32 v0, 0x4f7ffffe, v0
	v_cvt_u32_f32_e32 v0, v0
	s_nop 0
	v_readfirstlane_b32 s43, v0
	s_mul_i32 s42, s42, s43
	s_mul_hi_u32 s42, s43, s42
	s_add_i32 s43, s43, s42
	s_mul_hi_u32 s42, s22, s43
	s_mul_i32 s43, s42, s36
	s_sub_i32 s22, s22, s43
	s_add_i32 s44, s42, 1
	s_sub_i32 s43, s22, s36
	s_cmp_ge_u32 s22, s36
	s_cselect_b32 s42, s44, s42
	s_cselect_b32 s22, s43, s22
	s_add_i32 s43, s42, 1
	s_cmp_ge_u32 s22, s36
	s_cselect_b32 s22, s43, s42
	s_xor_b32 s22, s22, s37
	s_sub_i32 s22, s22, s37
	s_mul_i32 s25, s22, s25
	s_sub_i32 s23, s23, s25
	s_add_i32 s24, s23, s24
